# baseline (speedup 1.0000x reference)
_Z11mega_kernel1P:
	s_mov_b64 s[36:37], s[0:1]
	s_lshr_b32 s32, s2, 3
	s_cmp_lt_u32 s32, 32
	s_cbranch_scc1 .Lprio_done
	s_setprio 1
.Lprio_done:
	s_load_dwordx2 s[0:1], s[0:1], 0xc8
	s_add_u32 s60, s36, 0xd0
	s_addc_u32 s61, s37, 0
	s_mov_b64 s[4:5], 0
	s_waitcnt lgkmcnt(0)
	s_cmp_eq_u64 s[0:1], 0
	s_cbranch_scc1 .LBB0_2
	v_and_b32_e32 v170, 0x3ff, v0
	s_load_dword s34, s[36:37], 0xd0
	s_andn2_b64 vcc, exec, s[4:5]
	s_cbranch_vccz .LBB0_3
	s_branch .LBB0_14
